# c30: SSD pass-3 output-row loop unrolled (state fragments read once, both 16-row halves' reads issued together, two MFMA chains interleaved)
# speedup vs baseline: 1.0399x; 1.0046x over previous
; __device__ __forceinline__ float bflo(unsigned u) { return __uint_as_float(u << 16); }
; __device__ __forceinline__ float bfhi(unsigned u) { return __uint_as_float(u & 0xffff0000u); }
; __device__ __forceinline__ v4i16 tr16(const unsigned char* p) { return __builtin_amdgcn_ds_read_tr16_b64_v4i16((LDSAS v4i16*)p); }
; __device__ __forceinline__ bf16x8 cat8(v4i16 a, v4i16 b) { return (bf16x8){a[0], a[1], a[2], a[3], b[0], b[1], b[2], b[3]}; }
; __device__ __forceinline__ void st4bf(bf16_t* dst, f32x4 v) { u32x2 pk; pk.x = pk2(v.x, v.y); pk.y = pk2(v.z, v.w); *(u32x2*)dst = pk; }
; template <int PASS>
; __device__ void ssd_item(const Params& p, int item, int l, unsigned char* smem) {
;     ...
;                 st4bf(Gs + ii * 40 + 16 * jt + 4 * kq, gv);
;             }
;             __syncthreads();
;             const unsigned char* xtr = (const unsigned char*)Xs + (8 * kq + (idx >> 2)) * 144 + (16 * w + 4 * (idx & 3)) * 2;
;             const bf16x8 xf = cat8(tr16(xtr), tr16(xtr + 4 * 144));
; #pragma unroll 1
;             for (int it2 = 0; it2 < 2; ++it2) {
;                 const int ii = 16 * it2 + idx;
;                 const bf16x8 gf = *(const bf16x8*)(Gs + ii * 40 + 8 * kq);
;                 f32x4 yd = (f32x4){0.f, 0.f, 0.f, 0.f}, yo = (f32x4){0.f, 0.f, 0.f, 0.f};
;                 bf16x8 sf[4], cf[4];
; #pragma unroll
;                 for (int ks = 0; ks < 4; ++ks) { sf[ks] = *(const bf16x8*)(Sb + (16 * w + idx) * 136 + ks * 32 + kq * 8); cf[ks] = *(const bf16x8*)(Cs + ii * 136 + ks * 32 + kq * 8); }
;                 __builtin_amdgcn_sched_barrier(0);
;                 yd = __builtin_amdgcn_mfma_f32_16x16x32_bf16(xf, gf, yd, 0, 0, 0);
; #pragma unroll
;                 for (int ks = 0; ks < 4; ++ks) yo = __builtin_amdgcn_mfma_f32_16x16x32_bf16(sf[ks], cf[ks], yo, 0, 0, 0);
;                 __builtin_amdgcn_sched_barrier(0);
;                 f32x4 y = yd + yo * s_rs[ii];
;                 if (dir == 0) { const u32x2 xv = *(const u32x2*)(Xs + ii * 72 + 16 * w + 4 * kq);
;                     y.x += Dh * bflo(xv.x); y.y += Dh * bfhi(xv.x); y.z += Dh * bflo(xv.y); y.w += Dh * bfhi(xv.y); }
;                 st4bf(Y + (tokb + t0 + ii) * 512 + h * 64 + 16 * w + 4 * kq, y);
;             }
.LBB0_930:
	s_or_b64 exec, exec, s[66:67]
	v_cvt_pk_bf16_f32 v32, v38, v32
	v_cvt_pk_bf16_f32 v33, v36, v33
	ds_write_b64 v74, v[32:33] offset:26624
	s_waitcnt lgkmcnt(0)
	s_barrier
	ds_read_b64_tr_b16 v[32:33], v94 offset:17408
	ds_read_b64_tr_b16 v[34:35], v94 offset:17984
	s_add_u32 s21, s94, s21
	s_addc_u32 s22, s95, 0
	v_mad_u32_u24 v36, v53, s1, v56
	v_mad_u32_u24 v50, v53, s0, v56
	v_lshl_add_u32 v185, v53, 2, v40
	ds_read_b32 v186, v185 offset:48640
	v_mad_u32_u24 v188, v53, s3, v76
	ds_read_b64 v[188:189], v188 offset:17408
	ds_read_b128 v[36:39], v36 offset:26624
	ds_read_b128 v[42:45], v50 offset:8704
	ds_read_b128 v[46:49], v75 offset:29184
	ds_read_b128 v[96:99], v75 offset:29248
	ds_read_b128 v[100:103], v50 offset:8768
	ds_read_b128 v[104:107], v50 offset:8832
	ds_read_b128 v[108:111], v75 offset:29312
	ds_read_b128 v[112:115], v75 offset:29376
	ds_read_b128 v[116:119], v50 offset:8896
	v_or_b32_e32 v244, 16, v53
	v_mad_u32_u24 v245, v244, s1, v56
	v_mad_u32_u24 v246, v244, s0, v56
	v_lshl_add_u32 v247, v244, 2, v40
	ds_read_b32 v240, v247 offset:48640
	v_mad_u32_u24 v247, v244, s3, v76
	ds_read_b64 v[242:243], v247 offset:17408
	ds_read_b128 v[190:193], v245 offset:26624
	ds_read_b128 v[194:197], v246 offset:8704
	ds_read_b128 v[198:201], v246 offset:8768
	ds_read_b128 v[202:205], v246 offset:8832
	ds_read_b128 v[236:239], v246 offset:8896
	s_waitcnt lgkmcnt(0)
	v_mfma_f32_16x16x32_bf16 v[42:45], v[46:49], v[42:45], 0
	v_mfma_f32_16x16x32_bf16 v[194:197], v[46:49], v[194:197], 0
	v_mfma_f32_16x16x32_bf16 v[42:45], v[96:99], v[100:103], v[42:45]
	v_mfma_f32_16x16x32_bf16 v[194:197], v[96:99], v[198:201], v[194:197]
	v_mfma_f32_16x16x32_bf16 v[42:45], v[108:111], v[104:107], v[42:45]
	v_mfma_f32_16x16x32_bf16 v[194:197], v[108:111], v[202:205], v[194:197]
	v_mfma_f32_16x16x32_bf16 v[42:45], v[112:115], v[116:119], v[42:45]
	v_mfma_f32_16x16x32_bf16 v[194:197], v[112:115], v[236:239], v[194:197]
	v_mfma_f32_16x16x32_bf16 v[46:49], v[32:35], v[36:39], 0
	v_mfma_f32_16x16x32_bf16 v[96:99], v[32:35], v[190:193], 0
	s_nop 7
	s_nop 3
	v_pk_fma_f32 v[36:37], v[44:45], v[186:187], v[48:49] op_sel_hi:[1,0,1]
	v_pk_fma_f32 v[38:39], v[42:43], v[186:187], v[46:47] op_sel_hi:[1,0,1]
	v_pk_fma_f32 v[190:191], v[196:197], v[240:241], v[98:99] op_sel_hi:[1,0,1]
	v_pk_fma_f32 v[192:193], v[194:195], v[240:241], v[96:97] op_sel_hi:[1,0,1]
	s_andn2_b64 vcc, exec, s[36:37]
	s_cbranch_vccnz .Lssd3_nod
	v_lshlrev_b32_e32 v44, 16, v188
	v_and_b32_e32 v45, 0xffff0000, v188
	v_lshlrev_b32_e32 v42, 16, v189
	v_and_b32_e32 v43, 0xffff0000, v189
	v_pk_fma_f32 v[38:39], v[54:55], v[44:45], v[38:39]
	v_pk_fma_f32 v[36:37], v[54:55], v[42:43], v[36:37]
	v_lshlrev_b32_e32 v44, 16, v242
	v_and_b32_e32 v45, 0xffff0000, v242
	v_lshlrev_b32_e32 v42, 16, v243
	v_and_b32_e32 v43, 0xffff0000, v243
	v_pk_fma_f32 v[192:193], v[54:55], v[44:45], v[192:193]
	v_pk_fma_f32 v[190:191], v[54:55], v[42:43], v[190:191]
.Lssd3_nod:
	v_mov_b32_e32 v43, s22
	v_or_b32_e32 v42, s21, v53
	v_lshlrev_b64 v[42:43], 10, v[42:43]
	v_lshl_add_u64 v[42:43], v[60:61], 0, v[42:43]
	v_cvt_pk_bf16_f32 v38, v38, v39
	v_cvt_pk_bf16_f32 v39, v36, v37
	global_store_dwordx2 v[42:43], v[38:39], off
	v_mov_b32_e32 v45, s22
	v_or_b32_e32 v44, s21, v244
	v_lshlrev_b64 v[44:45], 10, v[44:45]
	v_lshl_add_u64 v[44:45], v[60:61], 0, v[44:45]
	v_cvt_pk_bf16_f32 v192, v192, v193
	v_cvt_pk_bf16_f32 v193, v190, v191
	global_store_dwordx2 v[44:45], v[192:193], off
	s_branch .LBB0_913
